# LayerNorm (LN0, LN1, one LN2 variant): gamma/beta loads of all four column chunks issued together, the three per-chunk vmcnt(0) waits (round trip + store acks) removed
# speedup vs baseline: 1.0165x; 1.0013x over previous
.LBB0_132:
	s_or_b64 exec, exec, s[2:3]
	global_load_dwordx4 v[156:159], v[132:133], off
	global_load_dwordx4 v[160:163], v[134:135], off
	global_load_dwordx4 v[176:179], v[132:133], off offset:1024
	global_load_dwordx4 v[180:183], v[134:135], off offset:1024
	global_load_dwordx4 v[184:187], v[132:133], off offset:2048
	global_load_dwordx4 v[188:191], v[134:135], off offset:2048
	global_load_dwordx4 v[192:195], v[132:133], off offset:3072
	global_load_dwordx4 v[196:199], v[134:135], off offset:3072
	v_pk_mul_f32 v[168:169], v[106:107], v[120:121] op_sel_hi:[1,0]
	v_lshl_add_u64 v[106:107], s[54:55], 0, v[136:137]
	v_pk_mul_f32 v[164:165], v[18:19], v[56:57] op_sel_hi:[1,0]
	v_add_co_u32_e32 v18, vcc, s59, v106
	v_pk_mul_f32 v[170:171], v[20:21], v[56:57] op_sel_hi:[1,0]
	s_nop 0
	v_addc_co_u32_e32 v19, vcc, 0, v107, vcc
	v_add_co_u32_e32 v20, vcc, s68, v106
	v_pk_mul_f32 v[166:167], v[22:23], v[84:85] op_sel_hi:[1,0]
	s_nop 0
	v_addc_co_u32_e32 v21, vcc, 0, v107, vcc
	v_add_co_u32_e32 v22, vcc, s69, v106
	v_pk_mul_f32 v[110:111], v[110:111], v[124:125] op_sel_hi:[1,0]
	v_pk_mul_f32 v[114:115], v[114:115], v[128:129] op_sel_hi:[1,0]
	v_pk_mul_f32 v[118:119], v[118:119], v[150:151] op_sel_hi:[1,0]
	v_pk_mul_f32 v[122:123], v[122:123], v[152:153] op_sel_hi:[1,0]
	v_pk_mul_f32 v[126:127], v[126:127], v[154:155] op_sel_hi:[1,0]
	v_pk_mul_f32 v[142:143], v[142:143], v[84:85] op_sel_hi:[1,0]
	v_pk_mul_f32 v[108:109], v[108:109], v[120:121] op_sel_hi:[1,0]
	v_pk_mul_f32 v[112:113], v[112:113], v[124:125] op_sel_hi:[1,0]
	v_pk_mul_f32 v[116:117], v[116:117], v[128:129] op_sel_hi:[1,0]
	v_pk_mul_f32 v[144:145], v[144:145], v[150:151] op_sel_hi:[1,0]
	v_pk_mul_f32 v[146:147], v[146:147], v[152:153] op_sel_hi:[1,0]
	v_pk_mul_f32 v[148:149], v[148:149], v[154:155] op_sel_hi:[1,0]
	v_addc_co_u32_e32 v23, vcc, 0, v107, vcc
	v_add_co_u32_e32 v106, vcc, s70, v106
	v_pk_mul_f32 v[10:11], v[10:11], v[56:57] op_sel_hi:[1,0]
	s_nop 0
	v_addc_co_u32_e32 v107, vcc, 0, v107, vcc
	v_pk_mul_f32 v[12:13], v[12:13], v[56:57] op_sel_hi:[1,0]
	v_pk_mul_f32 v[14:15], v[14:15], v[84:85] op_sel_hi:[1,0]
	v_pk_mul_f32 v[70:71], v[70:71], v[120:121] op_sel_hi:[1,0]
	v_pk_mul_f32 v[86:87], v[86:87], v[124:125] op_sel_hi:[1,0]
	v_pk_mul_f32 v[90:91], v[90:91], v[128:129] op_sel_hi:[1,0]
	v_pk_mul_f32 v[94:95], v[94:95], v[150:151] op_sel_hi:[1,0]
	v_pk_mul_f32 v[98:99], v[98:99], v[152:153] op_sel_hi:[1,0]
	v_pk_mul_f32 v[102:103], v[102:103], v[154:155] op_sel_hi:[1,0]
	v_pk_mul_f32 v[72:73], v[72:73], v[120:121] op_sel_hi:[1,0]
	v_pk_mul_f32 v[88:89], v[88:89], v[124:125] op_sel_hi:[1,0]
	v_pk_mul_f32 v[92:93], v[92:93], v[128:129] op_sel_hi:[1,0]
	v_pk_mul_f32 v[96:97], v[96:97], v[150:151] op_sel_hi:[1,0]
	v_pk_mul_f32 v[100:101], v[100:101], v[152:153] op_sel_hi:[1,0]
	v_pk_mul_f32 v[104:105], v[104:105], v[154:155] op_sel_hi:[1,0]
	v_pk_mul_f32 v[8:9], v[8:9], v[56:57] op_sel_hi:[1,0]
	v_pk_mul_f32 v[6:7], v[6:7], v[56:57] op_sel_hi:[1,0]
	v_pk_mul_f32 v[46:47], v[46:47], v[84:85] op_sel_hi:[1,0]
	v_pk_mul_f32 v[58:59], v[58:59], v[120:121] op_sel_hi:[1,0]
	v_pk_mul_f32 v[62:63], v[62:63], v[124:125] op_sel_hi:[1,0]
	v_pk_mul_f32 v[66:67], v[66:67], v[128:129] op_sel_hi:[1,0]
	v_pk_mul_f32 v[74:75], v[74:75], v[150:151] op_sel_hi:[1,0]
	v_pk_mul_f32 v[78:79], v[78:79], v[152:153] op_sel_hi:[1,0]
	v_pk_mul_f32 v[52:53], v[52:53], v[154:155] op_sel_hi:[1,0]
	s_add_i32 s56, s56, s58
	v_pk_mul_f32 v[4:5], v[4:5], v[56:57] op_sel_hi:[1,0]
	v_pk_mul_f32 v[2:3], v[2:3], v[56:57] op_sel_hi:[1,0]
	s_add_u32 s60, s60, s62
	v_pk_mul_f32 v[24:25], v[24:25], v[120:121] op_sel_hi:[1,0]
	v_pk_mul_f32 v[28:29], v[28:29], v[124:125] op_sel_hi:[1,0]
	v_pk_mul_f32 v[32:33], v[32:33], v[128:129] op_sel_hi:[1,0]
	v_pk_mul_f32 v[36:37], v[36:37], v[150:151] op_sel_hi:[1,0]
	v_pk_mul_f32 v[40:41], v[40:41], v[152:153] op_sel_hi:[1,0]
	v_pk_mul_f32 v[44:45], v[44:45], v[154:155] op_sel_hi:[1,0]
	s_addc_u32 s61, s61, s63
	v_lshl_add_u64 v[136:137], v[136:137], 0, s[64:65]
	s_cmp_lt_i32 s56, 0x8000
	v_lshl_add_u64 v[138:139], v[138:139], 0, s[66:67]
	s_waitcnt vmcnt(0) lgkmcnt(0)
	v_pk_fma_f32 v[170:171], v[170:171], v[158:159], v[162:163]
	v_pk_fma_f32 v[164:165], v[164:165], v[156:157], v[160:161]
	v_pk_fma_f32 v[142:143], v[142:143], v[158:159], v[162:163]
	v_pk_fma_f32 v[166:167], v[166:167], v[156:157], v[160:161]
	v_pk_fma_f32 v[108:109], v[108:109], v[158:159], v[162:163]
	v_pk_fma_f32 v[168:169], v[168:169], v[156:157], v[160:161]
	v_pk_fma_f32 v[112:113], v[112:113], v[158:159], v[162:163]
	v_pk_fma_f32 v[110:111], v[110:111], v[156:157], v[160:161]
	v_pk_fma_f32 v[116:117], v[116:117], v[158:159], v[162:163]
	v_pk_fma_f32 v[114:115], v[114:115], v[156:157], v[160:161]
	v_pk_fma_f32 v[144:145], v[144:145], v[158:159], v[162:163]
	v_pk_fma_f32 v[118:119], v[118:119], v[156:157], v[160:161]
	v_pk_fma_f32 v[146:147], v[146:147], v[158:159], v[162:163]
	v_pk_fma_f32 v[122:123], v[122:123], v[156:157], v[160:161]
	v_pk_fma_f32 v[148:149], v[148:149], v[158:159], v[162:163]
	v_pk_fma_f32 v[126:127], v[126:127], v[156:157], v[160:161]
	v_cvt_pk_bf16_f32 v156, v164, v165
	v_cvt_pk_bf16_f32 v157, v170, v171
	v_cvt_pk_bf16_f32 v158, v166, v167
	v_cvt_pk_bf16_f32 v159, v142, v143
	v_cvt_pk_bf16_f32 v142, v168, v169
	v_cvt_pk_bf16_f32 v143, v108, v109
	v_cvt_pk_bf16_f32 v108, v110, v111
	v_cvt_pk_bf16_f32 v109, v112, v113
	v_cvt_pk_bf16_f32 v110, v114, v115
	v_cvt_pk_bf16_f32 v111, v116, v117
	v_cvt_pk_bf16_f32 v112, v118, v119
	v_cvt_pk_bf16_f32 v113, v144, v145
	v_cvt_pk_bf16_f32 v114, v122, v123
	v_cvt_pk_bf16_f32 v115, v146, v147
	v_cvt_pk_bf16_f32 v116, v126, v127
	v_cvt_pk_bf16_f32 v117, v148, v149
	global_store_dwordx2 v[18:19], v[156:157], off
	global_store_dwordx2 v[18:19], v[158:159], off offset:2048
	global_store_dwordx2 v[20:21], v[142:143], off
	global_store_dwordx2 v[20:21], v[108:109], off offset:2048
	global_store_dwordx2 v[22:23], v[110:111], off
	global_store_dwordx2 v[22:23], v[112:113], off offset:2048
	global_store_dwordx2 v[106:107], v[114:115], off
	global_store_dwordx2 v[106:107], v[116:117], off offset:2048
	s_nop 0
	v_pk_mul_f32 v[116:117], v[140:141], v[84:85] op_sel_hi:[1,0]
	v_pk_fma_f32 v[12:13], v[12:13], v[178:179], v[182:183]
	v_pk_fma_f32 v[10:11], v[10:11], v[176:177], v[180:181]
	v_pk_fma_f32 v[116:117], v[116:117], v[178:179], v[182:183]
	v_pk_fma_f32 v[14:15], v[14:15], v[176:177], v[180:181]
	v_pk_fma_f32 v[72:73], v[72:73], v[178:179], v[182:183]
	v_pk_fma_f32 v[70:71], v[70:71], v[176:177], v[180:181]
	v_pk_fma_f32 v[88:89], v[88:89], v[178:179], v[182:183]
	v_pk_fma_f32 v[86:87], v[86:87], v[176:177], v[180:181]
	v_pk_fma_f32 v[92:93], v[92:93], v[178:179], v[182:183]
	v_pk_fma_f32 v[90:91], v[90:91], v[176:177], v[180:181]
	v_pk_fma_f32 v[96:97], v[96:97], v[178:179], v[182:183]
	v_pk_fma_f32 v[94:95], v[94:95], v[176:177], v[180:181]
	v_pk_fma_f32 v[100:101], v[100:101], v[178:179], v[182:183]
	v_pk_fma_f32 v[98:99], v[98:99], v[176:177], v[180:181]
	v_pk_fma_f32 v[104:105], v[104:105], v[178:179], v[182:183]
	v_pk_fma_f32 v[102:103], v[102:103], v[176:177], v[180:181]
	v_cvt_pk_bf16_f32 v10, v10, v11
	v_cvt_pk_bf16_f32 v11, v12, v13
	v_cvt_pk_bf16_f32 v12, v14, v15
	v_cvt_pk_bf16_f32 v13, v116, v117
	v_cvt_pk_bf16_f32 v14, v70, v71
	v_cvt_pk_bf16_f32 v15, v72, v73
	v_cvt_pk_bf16_f32 v70, v86, v87
	v_cvt_pk_bf16_f32 v71, v88, v89
	v_cvt_pk_bf16_f32 v72, v90, v91
	v_cvt_pk_bf16_f32 v73, v92, v93
	v_cvt_pk_bf16_f32 v86, v94, v95
	v_cvt_pk_bf16_f32 v87, v96, v97
	v_cvt_pk_bf16_f32 v88, v98, v99
	v_cvt_pk_bf16_f32 v89, v100, v101
	v_cvt_pk_bf16_f32 v90, v102, v103
	v_cvt_pk_bf16_f32 v91, v104, v105
	global_store_dwordx2 v[18:19], v[10:11], off offset:512
	global_store_dwordx2 v[18:19], v[12:13], off offset:2560
	global_store_dwordx2 v[20:21], v[14:15], off offset:512
	global_store_dwordx2 v[20:21], v[70:71], off offset:2560
	global_store_dwordx2 v[22:23], v[72:73], off offset:512
	global_store_dwordx2 v[22:23], v[86:87], off offset:2560
	global_store_dwordx2 v[106:107], v[88:89], off offset:512
	global_store_dwordx2 v[106:107], v[90:91], off offset:2560
	s_nop 0
	v_pk_mul_f32 v[14:15], v[48:49], v[84:85] op_sel_hi:[1,0]
	v_pk_mul_f32 v[48:49], v[60:61], v[120:121] op_sel_hi:[1,0]
	v_pk_mul_f32 v[60:61], v[64:65], v[124:125] op_sel_hi:[1,0]
	v_pk_mul_f32 v[64:65], v[68:69], v[128:129] op_sel_hi:[1,0]
	v_pk_mul_f32 v[68:69], v[76:77], v[150:151] op_sel_hi:[1,0]
	v_pk_mul_f32 v[76:77], v[80:81], v[152:153] op_sel_hi:[1,0]
	v_pk_mul_f32 v[80:81], v[82:83], v[154:155] op_sel_hi:[1,0]
	v_pk_fma_f32 v[8:9], v[8:9], v[186:187], v[190:191]
	v_pk_fma_f32 v[6:7], v[6:7], v[184:185], v[188:189]
	v_pk_fma_f32 v[14:15], v[14:15], v[186:187], v[190:191]
	v_pk_fma_f32 v[46:47], v[46:47], v[184:185], v[188:189]
	v_pk_fma_f32 v[48:49], v[48:49], v[186:187], v[190:191]
	v_pk_fma_f32 v[58:59], v[58:59], v[184:185], v[188:189]
	v_pk_fma_f32 v[60:61], v[60:61], v[186:187], v[190:191]
	v_pk_fma_f32 v[62:63], v[62:63], v[184:185], v[188:189]
	v_pk_fma_f32 v[64:65], v[64:65], v[186:187], v[190:191]
	v_pk_fma_f32 v[66:67], v[66:67], v[184:185], v[188:189]
	v_pk_fma_f32 v[68:69], v[68:69], v[186:187], v[190:191]
	v_pk_fma_f32 v[74:75], v[74:75], v[184:185], v[188:189]
	v_pk_fma_f32 v[76:77], v[76:77], v[186:187], v[190:191]
	v_pk_fma_f32 v[78:79], v[78:79], v[184:185], v[188:189]
	v_pk_fma_f32 v[12:13], v[52:53], v[186:187], v[190:191]
	v_pk_fma_f32 v[10:11], v[80:81], v[184:185], v[188:189]
	v_cvt_pk_bf16_f32 v6, v6, v7
	v_cvt_pk_bf16_f32 v7, v8, v9
	v_cvt_pk_bf16_f32 v8, v46, v47
	v_cvt_pk_bf16_f32 v9, v14, v15
	v_cvt_pk_bf16_f32 v14, v58, v59
	v_cvt_pk_bf16_f32 v15, v48, v49
	v_cvt_pk_bf16_f32 v46, v62, v63
	v_cvt_pk_bf16_f32 v47, v60, v61
	v_cvt_pk_bf16_f32 v48, v66, v67
	v_cvt_pk_bf16_f32 v49, v64, v65
	v_cvt_pk_bf16_f32 v52, v74, v75
	v_cvt_pk_bf16_f32 v53, v68, v69
	v_cvt_pk_bf16_f32 v58, v78, v79
	v_cvt_pk_bf16_f32 v59, v76, v77
	v_cvt_pk_bf16_f32 v10, v10, v11
	v_cvt_pk_bf16_f32 v11, v12, v13
	global_store_dwordx2 v[18:19], v[6:7], off offset:1024
	global_store_dwordx2 v[18:19], v[8:9], off offset:3072
	global_store_dwordx2 v[20:21], v[14:15], off offset:1024
	global_store_dwordx2 v[20:21], v[46:47], off offset:3072
	global_store_dwordx2 v[22:23], v[48:49], off offset:1024
	global_store_dwordx2 v[22:23], v[52:53], off offset:3072
	global_store_dwordx2 v[106:107], v[58:59], off offset:1024
	global_store_dwordx2 v[106:107], v[10:11], off offset:3072
	s_nop 0
	v_pk_mul_f32 v[14:15], v[16:17], v[84:85] op_sel_hi:[1,0]
	v_pk_mul_f32 v[16:17], v[26:27], v[84:85] op_sel_hi:[1,0]
	v_pk_mul_f32 v[26:27], v[30:31], v[120:121] op_sel_hi:[1,0]
	v_pk_mul_f32 v[30:31], v[34:35], v[124:125] op_sel_hi:[1,0]
	v_pk_mul_f32 v[34:35], v[38:39], v[128:129] op_sel_hi:[1,0]
	v_pk_mul_f32 v[38:39], v[42:43], v[150:151] op_sel_hi:[1,0]
	v_pk_mul_f32 v[42:43], v[50:51], v[152:153] op_sel_hi:[1,0]
	v_pk_mul_f32 v[46:47], v[54:55], v[154:155] op_sel_hi:[1,0]
	v_pk_fma_f32 v[4:5], v[4:5], v[194:195], v[198:199]
	v_pk_fma_f32 v[2:3], v[2:3], v[192:193], v[196:197]
	v_pk_fma_f32 v[14:15], v[14:15], v[194:195], v[198:199]
	v_pk_fma_f32 v[16:17], v[16:17], v[192:193], v[196:197]
	v_pk_fma_f32 v[24:25], v[24:25], v[194:195], v[198:199]
	v_pk_fma_f32 v[26:27], v[26:27], v[192:193], v[196:197]
	v_pk_fma_f32 v[28:29], v[28:29], v[194:195], v[198:199]
	v_pk_fma_f32 v[30:31], v[30:31], v[192:193], v[196:197]
	v_pk_fma_f32 v[32:33], v[32:33], v[194:195], v[198:199]
	v_pk_fma_f32 v[34:35], v[34:35], v[192:193], v[196:197]
	v_pk_fma_f32 v[36:37], v[36:37], v[194:195], v[198:199]
	v_pk_fma_f32 v[38:39], v[38:39], v[192:193], v[196:197]
	v_pk_fma_f32 v[40:41], v[40:41], v[194:195], v[198:199]
	v_pk_fma_f32 v[42:43], v[42:43], v[192:193], v[196:197]
	v_pk_fma_f32 v[8:9], v[44:45], v[194:195], v[198:199]
	v_pk_fma_f32 v[6:7], v[46:47], v[192:193], v[196:197]
	v_cvt_pk_bf16_f32 v2, v2, v3
	v_cvt_pk_bf16_f32 v3, v4, v5
	v_cvt_pk_bf16_f32 v4, v16, v17
	v_cvt_pk_bf16_f32 v5, v14, v15
	v_cvt_pk_bf16_f32 v10, v26, v27
	v_cvt_pk_bf16_f32 v11, v24, v25
	v_cvt_pk_bf16_f32 v12, v30, v31
	v_cvt_pk_bf16_f32 v13, v28, v29
	v_cvt_pk_bf16_f32 v14, v34, v35
	v_cvt_pk_bf16_f32 v15, v32, v33
	v_cvt_pk_bf16_f32 v16, v38, v39
	v_cvt_pk_bf16_f32 v17, v36, v37
	v_cvt_pk_bf16_f32 v24, v42, v43
	v_cvt_pk_bf16_f32 v25, v40, v41
	v_cvt_pk_bf16_f32 v6, v6, v7
	v_cvt_pk_bf16_f32 v7, v8, v9
	global_store_dwordx2 v[18:19], v[2:3], off offset:1536
	global_store_dwordx2 v[18:19], v[4:5], off offset:3584
	global_store_dwordx2 v[20:21], v[10:11], off offset:1536
	global_store_dwordx2 v[20:21], v[12:13], off offset:3584
	global_store_dwordx2 v[22:23], v[14:15], off offset:1536
	global_store_dwordx2 v[22:23], v[16:17], off offset:3584
	global_store_dwordx2 v[106:107], v[24:25], off offset:1536
	global_store_dwordx2 v[106:107], v[6:7], off offset:3584
	s_cbranch_scc0 .LBB0_149

.LBB0_1222:
	s_or_b64 exec, exec, s[6:7]
	global_load_dwordx4 v[126:129], v[134:135], off
	global_load_dwordx4 v[130:133], v[136:137], off
	global_load_dwordx4 v[176:179], v[134:135], off offset:1024
	global_load_dwordx4 v[180:183], v[136:137], off offset:1024
	global_load_dwordx4 v[184:187], v[134:135], off offset:2048
	global_load_dwordx4 v[188:191], v[136:137], off offset:2048
	global_load_dwordx4 v[192:195], v[134:135], off offset:3072
	global_load_dwordx4 v[196:199], v[136:137], off offset:3072
	v_pk_mul_f32 v[94:95], v[150:151], v[74:75] op_sel_hi:[1,0]
	v_pk_mul_f32 v[104:105], v[104:105], v[74:75] op_sel_hi:[1,0]
	v_lshl_add_u64 v[62:63], s[8:9], 0, v[138:139]
	s_mov_b32 s6, 0x3a00000
	v_pk_mul_f32 v[96:97], v[96:97], v[78:79] op_sel_hi:[1,0]
	v_pk_mul_f32 v[64:65], v[64:65], v[74:75] op_sel_hi:[1,0]
	v_pk_mul_f32 v[34:35], v[34:35], v[74:75] op_sel_hi:[1,0]
	v_pk_mul_f32 v[32:33], v[32:33], v[74:75] op_sel_hi:[1,0]
	v_pk_mul_f32 v[2:3], v[2:3], v[74:75] op_sel_hi:[1,0]
	v_pk_mul_f32 v[0:1], v[0:1], v[74:75] op_sel_hi:[1,0]
	s_add_i32 s10, s10, s12
	s_add_u32 s14, s14, s16
	s_addc_u32 s15, s15, s17
	v_lshl_add_u64 v[138:139], v[138:139], 0, s[18:19]
	v_lshl_add_u64 v[140:141], v[140:141], 0, s[20:21]
	s_cmp_lt_i32 s10, 0x8000
	s_waitcnt vmcnt(0) lgkmcnt(0)
	v_pk_fma_f32 v[94:95], v[94:95], v[128:129], v[132:133]
	v_pk_fma_f32 v[104:105], v[104:105], v[126:127], v[130:131]
	v_cvt_pk_bf16_f32 v151, v94, v95
	v_pk_mul_f32 v[94:95], v[98:99], v[78:79] op_sel_hi:[1,0]
	v_cvt_pk_bf16_f32 v150, v104, v105
	v_add_co_u32_e32 v104, vcc, s6, v62
	v_pk_fma_f32 v[94:95], v[94:95], v[128:129], v[132:133]
	v_pk_fma_f32 v[96:97], v[96:97], v[126:127], v[130:131]
	v_addc_co_u32_e32 v105, vcc, 0, v63, vcc
	v_cvt_pk_bf16_f32 v96, v96, v97
	v_cvt_pk_bf16_f32 v97, v94, v95
	global_store_dwordx2 v[104:105], v[96:97], off offset:2048
	v_pk_mul_f32 v[94:95], v[152:153], v[82:83] op_sel_hi:[1,0]
	v_pk_mul_f32 v[96:97], v[108:109], v[82:83] op_sel_hi:[1,0]
	s_mov_b32 s6, 0x3a01000
	v_pk_fma_f32 v[94:95], v[94:95], v[128:129], v[132:133]
	v_pk_fma_f32 v[96:97], v[96:97], v[126:127], v[130:131]
	v_add_co_u32_e32 v108, vcc, s6, v62
	v_cvt_pk_bf16_f32 v96, v96, v97
	v_cvt_pk_bf16_f32 v97, v94, v95
	v_addc_co_u32_e32 v109, vcc, 0, v63, vcc
	global_store_dwordx2 v[108:109], v[96:97], off
	v_pk_mul_f32 v[94:95], v[154:155], v[86:87] op_sel_hi:[1,0]
	v_pk_mul_f32 v[96:97], v[100:101], v[86:87] op_sel_hi:[1,0]
	v_pk_fma_f32 v[94:95], v[94:95], v[128:129], v[132:133]
	v_pk_fma_f32 v[96:97], v[96:97], v[126:127], v[130:131]
	s_mov_b32 s6, 0x3a02000
	v_cvt_pk_bf16_f32 v96, v96, v97
	v_cvt_pk_bf16_f32 v97, v94, v95
	global_store_dwordx2 v[108:109], v[96:97], off offset:2048
	v_pk_mul_f32 v[94:95], v[156:157], v[90:91] op_sel_hi:[1,0]
	v_pk_mul_f32 v[96:97], v[116:117], v[90:91] op_sel_hi:[1,0]
	v_pk_fma_f32 v[94:95], v[94:95], v[128:129], v[132:133]
	v_pk_fma_f32 v[96:97], v[96:97], v[126:127], v[130:131]
	v_add_co_u32_e32 v116, vcc, s6, v62
	v_cvt_pk_bf16_f32 v96, v96, v97
	v_cvt_pk_bf16_f32 v97, v94, v95
	v_addc_co_u32_e32 v117, vcc, 0, v63, vcc
	global_store_dwordx2 v[116:117], v[96:97], off
	v_pk_mul_f32 v[94:95], v[158:159], v[102:103] op_sel_hi:[1,0]
	v_pk_mul_f32 v[96:97], v[112:113], v[102:103] op_sel_hi:[1,0]
	v_pk_fma_f32 v[94:95], v[94:95], v[128:129], v[132:133]
	v_pk_fma_f32 v[96:97], v[96:97], v[126:127], v[130:131]
	s_mov_b32 s6, 0x3a03000
	v_cvt_pk_bf16_f32 v96, v96, v97
	v_cvt_pk_bf16_f32 v97, v94, v95
	global_store_dwordx2 v[116:117], v[96:97], off offset:2048
	v_pk_mul_f32 v[94:95], v[160:161], v[114:115] op_sel_hi:[1,0]
	v_pk_mul_f32 v[96:97], v[124:125], v[114:115] op_sel_hi:[1,0]
	v_pk_fma_f32 v[94:95], v[94:95], v[128:129], v[132:133]
	v_pk_fma_f32 v[96:97], v[96:97], v[126:127], v[130:131]
	v_add_co_u32_e32 v112, vcc, s6, v62
	v_cvt_pk_bf16_f32 v96, v96, v97
	v_cvt_pk_bf16_f32 v97, v94, v95
	v_addc_co_u32_e32 v113, vcc, 0, v63, vcc
	v_pk_mul_f32 v[62:63], v[162:163], v[118:119] op_sel_hi:[1,0]
	v_pk_mul_f32 v[94:95], v[120:121], v[118:119] op_sel_hi:[1,0]
	v_pk_fma_f32 v[62:63], v[62:63], v[128:129], v[132:133]
	v_pk_fma_f32 v[94:95], v[94:95], v[126:127], v[130:131]
	global_store_dwordx2 v[104:105], v[150:151], off
	v_cvt_pk_bf16_f32 v94, v94, v95
	v_cvt_pk_bf16_f32 v95, v62, v63
	global_store_dwordx2 v[112:113], v[96:97], off
	global_store_dwordx2 v[112:113], v[94:95], off offset:2048
	s_nop 0
	v_pk_mul_f32 v[62:63], v[66:67], v[74:75] op_sel_hi:[1,0]
	v_pk_fma_f32 v[64:65], v[64:65], v[176:177], v[180:181]
	v_pk_fma_f32 v[62:63], v[62:63], v[178:179], v[182:183]
	v_cvt_pk_bf16_f32 v64, v64, v65
	v_cvt_pk_bf16_f32 v65, v62, v63
	global_store_dwordx2 v[104:105], v[64:65], off offset:512
	v_pk_mul_f32 v[62:63], v[106:107], v[78:79] op_sel_hi:[1,0]
	v_pk_mul_f32 v[64:65], v[68:69], v[78:79] op_sel_hi:[1,0]
	v_pk_fma_f32 v[62:63], v[62:63], v[178:179], v[182:183]
	v_pk_fma_f32 v[64:65], v[64:65], v[176:177], v[180:181]
	s_nop 0
	v_cvt_pk_bf16_f32 v64, v64, v65
	v_cvt_pk_bf16_f32 v65, v62, v63
	global_store_dwordx2 v[104:105], v[64:65], off offset:2560
	v_pk_mul_f32 v[62:63], v[110:111], v[82:83] op_sel_hi:[1,0]
	v_pk_mul_f32 v[64:65], v[72:73], v[82:83] op_sel_hi:[1,0]
	v_pk_fma_f32 v[62:63], v[62:63], v[178:179], v[182:183]
	v_pk_fma_f32 v[64:65], v[64:65], v[176:177], v[180:181]
	s_nop 0
	v_cvt_pk_bf16_f32 v64, v64, v65
	v_cvt_pk_bf16_f32 v65, v62, v63
	global_store_dwordx2 v[108:109], v[64:65], off offset:512
	v_pk_mul_f32 v[62:63], v[142:143], v[86:87] op_sel_hi:[1,0]
	v_pk_mul_f32 v[64:65], v[76:77], v[86:87] op_sel_hi:[1,0]
	v_pk_fma_f32 v[62:63], v[62:63], v[178:179], v[182:183]
	v_pk_fma_f32 v[64:65], v[64:65], v[176:177], v[180:181]
	s_nop 0
	v_cvt_pk_bf16_f32 v64, v64, v65
	v_cvt_pk_bf16_f32 v65, v62, v63
	global_store_dwordx2 v[108:109], v[64:65], off offset:2560
	v_pk_mul_f32 v[62:63], v[144:145], v[90:91] op_sel_hi:[1,0]
	v_pk_mul_f32 v[64:65], v[80:81], v[90:91] op_sel_hi:[1,0]
	v_pk_fma_f32 v[62:63], v[62:63], v[178:179], v[182:183]
	v_pk_fma_f32 v[64:65], v[64:65], v[176:177], v[180:181]
	s_nop 0
	v_cvt_pk_bf16_f32 v64, v64, v65
	v_cvt_pk_bf16_f32 v65, v62, v63
	global_store_dwordx2 v[116:117], v[64:65], off offset:512
	v_pk_mul_f32 v[62:63], v[146:147], v[102:103] op_sel_hi:[1,0]
	v_pk_mul_f32 v[64:65], v[84:85], v[102:103] op_sel_hi:[1,0]
	v_pk_fma_f32 v[62:63], v[62:63], v[178:179], v[182:183]
	v_pk_fma_f32 v[64:65], v[64:65], v[176:177], v[180:181]
	s_nop 0
	v_cvt_pk_bf16_f32 v64, v64, v65
	v_cvt_pk_bf16_f32 v65, v62, v63
	global_store_dwordx2 v[116:117], v[64:65], off offset:2560
	v_pk_mul_f32 v[62:63], v[148:149], v[114:115] op_sel_hi:[1,0]
	v_pk_mul_f32 v[64:65], v[88:89], v[114:115] op_sel_hi:[1,0]
	v_pk_fma_f32 v[62:63], v[62:63], v[178:179], v[182:183]
	v_pk_fma_f32 v[64:65], v[64:65], v[176:177], v[180:181]
	s_nop 0
	v_cvt_pk_bf16_f32 v64, v64, v65
	v_cvt_pk_bf16_f32 v65, v62, v63
	global_store_dwordx2 v[112:113], v[64:65], off offset:512
	v_pk_mul_f32 v[62:63], v[122:123], v[118:119] op_sel_hi:[1,0]
	v_pk_mul_f32 v[64:65], v[92:93], v[118:119] op_sel_hi:[1,0]
	v_pk_fma_f32 v[62:63], v[62:63], v[178:179], v[182:183]
	v_pk_fma_f32 v[64:65], v[64:65], v[176:177], v[180:181]
	s_nop 0
	v_cvt_pk_bf16_f32 v64, v64, v65
	v_cvt_pk_bf16_f32 v65, v62, v63
	global_store_dwordx2 v[112:113], v[64:65], off offset:2560
	s_nop 0
	v_pk_fma_f32 v[34:35], v[34:35], v[186:187], v[190:191]
	v_pk_fma_f32 v[32:33], v[32:33], v[184:185], v[188:189]
	s_nop 0
	v_cvt_pk_bf16_f32 v32, v32, v33
	v_cvt_pk_bf16_f32 v33, v34, v35
	global_store_dwordx2 v[104:105], v[32:33], off offset:1024
	v_pk_mul_f32 v[32:33], v[38:39], v[78:79] op_sel_hi:[1,0]
	v_pk_mul_f32 v[34:35], v[36:37], v[78:79] op_sel_hi:[1,0]
	v_pk_fma_f32 v[32:33], v[32:33], v[186:187], v[190:191]
	v_pk_fma_f32 v[34:35], v[34:35], v[184:185], v[188:189]
	s_nop 0
	v_cvt_pk_bf16_f32 v34, v34, v35
	v_cvt_pk_bf16_f32 v35, v32, v33
	global_store_dwordx2 v[104:105], v[34:35], off offset:3072
	v_pk_mul_f32 v[32:33], v[42:43], v[82:83] op_sel_hi:[1,0]
	v_pk_mul_f32 v[34:35], v[40:41], v[82:83] op_sel_hi:[1,0]
	v_pk_fma_f32 v[32:33], v[32:33], v[186:187], v[190:191]
	v_pk_fma_f32 v[34:35], v[34:35], v[184:185], v[188:189]
	s_nop 0
	v_cvt_pk_bf16_f32 v34, v34, v35
	v_cvt_pk_bf16_f32 v35, v32, v33
	global_store_dwordx2 v[108:109], v[34:35], off offset:1024
	v_pk_mul_f32 v[32:33], v[46:47], v[86:87] op_sel_hi:[1,0]
	v_pk_mul_f32 v[34:35], v[44:45], v[86:87] op_sel_hi:[1,0]
	v_pk_fma_f32 v[32:33], v[32:33], v[186:187], v[190:191]
	v_pk_fma_f32 v[34:35], v[34:35], v[184:185], v[188:189]
	s_nop 0
	v_cvt_pk_bf16_f32 v34, v34, v35
	v_cvt_pk_bf16_f32 v35, v32, v33
	global_store_dwordx2 v[108:109], v[34:35], off offset:3072
	v_pk_mul_f32 v[32:33], v[50:51], v[90:91] op_sel_hi:[1,0]
	v_pk_mul_f32 v[34:35], v[48:49], v[90:91] op_sel_hi:[1,0]
	v_pk_fma_f32 v[32:33], v[32:33], v[186:187], v[190:191]
	v_pk_fma_f32 v[34:35], v[34:35], v[184:185], v[188:189]
	s_nop 0
	v_cvt_pk_bf16_f32 v34, v34, v35
	v_cvt_pk_bf16_f32 v35, v32, v33
	global_store_dwordx2 v[116:117], v[34:35], off offset:1024
	v_pk_mul_f32 v[32:33], v[54:55], v[102:103] op_sel_hi:[1,0]
	v_pk_mul_f32 v[34:35], v[52:53], v[102:103] op_sel_hi:[1,0]
	v_pk_fma_f32 v[32:33], v[32:33], v[186:187], v[190:191]
	v_pk_fma_f32 v[34:35], v[34:35], v[184:185], v[188:189]
	s_nop 0
	v_cvt_pk_bf16_f32 v34, v34, v35
	v_cvt_pk_bf16_f32 v35, v32, v33
	global_store_dwordx2 v[116:117], v[34:35], off offset:3072
	v_pk_mul_f32 v[32:33], v[58:59], v[114:115] op_sel_hi:[1,0]
	v_pk_mul_f32 v[34:35], v[56:57], v[114:115] op_sel_hi:[1,0]
	v_pk_fma_f32 v[32:33], v[32:33], v[186:187], v[190:191]
	v_pk_fma_f32 v[34:35], v[34:35], v[184:185], v[188:189]
	s_nop 0
	v_cvt_pk_bf16_f32 v34, v34, v35
	v_cvt_pk_bf16_f32 v35, v32, v33
	global_store_dwordx2 v[112:113], v[34:35], off offset:1024
	v_pk_mul_f32 v[32:33], v[70:71], v[118:119] op_sel_hi:[1,0]
	v_pk_mul_f32 v[34:35], v[60:61], v[118:119] op_sel_hi:[1,0]
	v_pk_fma_f32 v[32:33], v[32:33], v[186:187], v[190:191]
	v_pk_fma_f32 v[34:35], v[34:35], v[184:185], v[188:189]
	s_nop 0
	v_cvt_pk_bf16_f32 v34, v34, v35
	v_cvt_pk_bf16_f32 v35, v32, v33
	global_store_dwordx2 v[112:113], v[34:35], off offset:3072
	s_nop 0
	v_pk_fma_f32 v[2:3], v[2:3], v[194:195], v[198:199]
	v_pk_fma_f32 v[0:1], v[0:1], v[192:193], v[196:197]
	s_nop 0
	v_cvt_pk_bf16_f32 v0, v0, v1
	v_cvt_pk_bf16_f32 v1, v2, v3
	global_store_dwordx2 v[104:105], v[0:1], off offset:1536
	v_pk_mul_f32 v[0:1], v[6:7], v[78:79] op_sel_hi:[1,0]
	v_pk_mul_f32 v[2:3], v[4:5], v[78:79] op_sel_hi:[1,0]
	v_pk_fma_f32 v[0:1], v[0:1], v[194:195], v[198:199]
	v_pk_fma_f32 v[2:3], v[2:3], v[192:193], v[196:197]
	s_nop 0
	v_cvt_pk_bf16_f32 v2, v2, v3
	v_cvt_pk_bf16_f32 v3, v0, v1
	global_store_dwordx2 v[104:105], v[2:3], off offset:3584
	v_pk_mul_f32 v[0:1], v[10:11], v[82:83] op_sel_hi:[1,0]
	v_pk_mul_f32 v[2:3], v[8:9], v[82:83] op_sel_hi:[1,0]
	v_pk_fma_f32 v[0:1], v[0:1], v[194:195], v[198:199]
	v_pk_fma_f32 v[2:3], v[2:3], v[192:193], v[196:197]
	s_nop 0
	v_cvt_pk_bf16_f32 v2, v2, v3
	v_cvt_pk_bf16_f32 v3, v0, v1
	global_store_dwordx2 v[108:109], v[2:3], off offset:1536
	v_pk_mul_f32 v[0:1], v[14:15], v[86:87] op_sel_hi:[1,0]
	v_pk_mul_f32 v[2:3], v[12:13], v[86:87] op_sel_hi:[1,0]
	v_pk_fma_f32 v[0:1], v[0:1], v[194:195], v[198:199]
	v_pk_fma_f32 v[2:3], v[2:3], v[192:193], v[196:197]
	s_nop 0
	v_cvt_pk_bf16_f32 v2, v2, v3
	v_cvt_pk_bf16_f32 v3, v0, v1
	global_store_dwordx2 v[108:109], v[2:3], off offset:3584
	v_pk_mul_f32 v[0:1], v[18:19], v[90:91] op_sel_hi:[1,0]
	v_pk_mul_f32 v[2:3], v[16:17], v[90:91] op_sel_hi:[1,0]
	v_pk_fma_f32 v[0:1], v[0:1], v[194:195], v[198:199]
	v_pk_fma_f32 v[2:3], v[2:3], v[192:193], v[196:197]
	s_nop 0
	v_cvt_pk_bf16_f32 v2, v2, v3
	v_cvt_pk_bf16_f32 v3, v0, v1
	global_store_dwordx2 v[116:117], v[2:3], off offset:1536
	v_pk_mul_f32 v[0:1], v[22:23], v[102:103] op_sel_hi:[1,0]
	v_pk_mul_f32 v[2:3], v[20:21], v[102:103] op_sel_hi:[1,0]
	v_pk_fma_f32 v[0:1], v[0:1], v[194:195], v[198:199]
	v_pk_fma_f32 v[2:3], v[2:3], v[192:193], v[196:197]
	s_nop 0
	v_cvt_pk_bf16_f32 v2, v2, v3
	v_cvt_pk_bf16_f32 v3, v0, v1
	global_store_dwordx2 v[116:117], v[2:3], off offset:3584
	v_pk_mul_f32 v[0:1], v[26:27], v[114:115] op_sel_hi:[1,0]
	v_pk_mul_f32 v[2:3], v[24:25], v[114:115] op_sel_hi:[1,0]
	v_pk_fma_f32 v[0:1], v[0:1], v[194:195], v[198:199]
	v_pk_fma_f32 v[2:3], v[2:3], v[192:193], v[196:197]
	s_nop 0
	v_cvt_pk_bf16_f32 v2, v2, v3
	v_cvt_pk_bf16_f32 v3, v0, v1
	global_store_dwordx2 v[112:113], v[2:3], off offset:1536
	v_pk_mul_f32 v[0:1], v[30:31], v[118:119] op_sel_hi:[1,0]
	v_pk_mul_f32 v[2:3], v[28:29], v[118:119] op_sel_hi:[1,0]
	v_pk_fma_f32 v[0:1], v[0:1], v[194:195], v[198:199]
	v_pk_fma_f32 v[2:3], v[2:3], v[192:193], v[196:197]
	s_nop 0
	v_cvt_pk_bf16_f32 v2, v2, v3
	v_cvt_pk_bf16_f32 v3, v0, v1
	global_store_dwordx2 v[112:113], v[2:3], off offset:3584
	s_cbranch_scc0 .LBB0_1239

.LBB0_1558:
	s_or_b64 exec, exec, s[6:7]
	global_load_dwordx4 v[126:129], v[134:135], off
	global_load_dwordx4 v[130:133], v[136:137], off
	global_load_dwordx4 v[176:179], v[134:135], off offset:1024
	global_load_dwordx4 v[180:183], v[136:137], off offset:1024
	global_load_dwordx4 v[184:187], v[134:135], off offset:2048
	global_load_dwordx4 v[192:195], v[136:137], off offset:2048
	global_load_dwordx4 v[196:199], v[134:135], off offset:3072
	global_load_dwordx4 v[200:203], v[136:137], off offset:3072
	v_pk_mul_f32 v[94:95], v[150:151], v[74:75] op_sel_hi:[1,0]
	v_pk_mul_f32 v[104:105], v[104:105], v[74:75] op_sel_hi:[1,0]
	v_lshl_add_u64 v[62:63], s[0:1], 0, v[138:139]
	s_mov_b32 s6, 0x3a00000
	v_pk_mul_f32 v[96:97], v[96:97], v[78:79] op_sel_hi:[1,0]
	v_pk_mul_f32 v[64:65], v[64:65], v[74:75] op_sel_hi:[1,0]
	v_pk_mul_f32 v[34:35], v[34:35], v[74:75] op_sel_hi:[1,0]
	v_pk_mul_f32 v[32:33], v[32:33], v[74:75] op_sel_hi:[1,0]
	v_pk_mul_f32 v[2:3], v[2:3], v[74:75] op_sel_hi:[1,0]
	v_pk_mul_f32 v[0:1], v[0:1], v[74:75] op_sel_hi:[1,0]
	s_add_i32 s10, s10, s12
	s_add_u32 s14, s14, s16
	s_addc_u32 s15, s15, s17
	v_lshl_add_u64 v[138:139], v[138:139], 0, s[18:19]
	v_lshl_add_u64 v[140:141], v[140:141], 0, s[20:21]
	s_cmpk_gt_i32 s10, 0x7fff
	s_waitcnt vmcnt(0) lgkmcnt(0)
	v_pk_fma_f32 v[94:95], v[94:95], v[128:129], v[132:133]
	v_pk_fma_f32 v[104:105], v[104:105], v[126:127], v[130:131]
	v_cvt_pk_bf16_f32 v151, v94, v95
	v_pk_mul_f32 v[94:95], v[98:99], v[78:79] op_sel_hi:[1,0]
	v_cvt_pk_bf16_f32 v150, v104, v105
	v_add_co_u32_e32 v104, vcc, s6, v62
	v_pk_fma_f32 v[94:95], v[94:95], v[128:129], v[132:133]
	v_pk_fma_f32 v[96:97], v[96:97], v[126:127], v[130:131]
	v_addc_co_u32_e32 v105, vcc, 0, v63, vcc
	v_cvt_pk_bf16_f32 v96, v96, v97
	v_cvt_pk_bf16_f32 v97, v94, v95
	global_store_dwordx2 v[104:105], v[96:97], off offset:2048
	v_pk_mul_f32 v[94:95], v[152:153], v[82:83] op_sel_hi:[1,0]
	v_pk_mul_f32 v[96:97], v[108:109], v[82:83] op_sel_hi:[1,0]
	s_mov_b32 s6, 0x3a01000
	v_pk_fma_f32 v[94:95], v[94:95], v[128:129], v[132:133]
	v_pk_fma_f32 v[96:97], v[96:97], v[126:127], v[130:131]
	v_add_co_u32_e32 v108, vcc, s6, v62
	v_cvt_pk_bf16_f32 v96, v96, v97
	v_cvt_pk_bf16_f32 v97, v94, v95
	v_addc_co_u32_e32 v109, vcc, 0, v63, vcc
	global_store_dwordx2 v[108:109], v[96:97], off
	v_pk_mul_f32 v[94:95], v[154:155], v[86:87] op_sel_hi:[1,0]
	v_pk_mul_f32 v[96:97], v[100:101], v[86:87] op_sel_hi:[1,0]
	v_pk_fma_f32 v[94:95], v[94:95], v[128:129], v[132:133]
	v_pk_fma_f32 v[96:97], v[96:97], v[126:127], v[130:131]
	s_mov_b32 s6, 0x3a02000
	v_cvt_pk_bf16_f32 v96, v96, v97
	v_cvt_pk_bf16_f32 v97, v94, v95
	global_store_dwordx2 v[108:109], v[96:97], off offset:2048
	v_pk_mul_f32 v[94:95], v[156:157], v[90:91] op_sel_hi:[1,0]
	v_pk_mul_f32 v[96:97], v[116:117], v[90:91] op_sel_hi:[1,0]
	v_pk_fma_f32 v[94:95], v[94:95], v[128:129], v[132:133]
	v_pk_fma_f32 v[96:97], v[96:97], v[126:127], v[130:131]
	v_add_co_u32_e32 v116, vcc, s6, v62
	v_cvt_pk_bf16_f32 v96, v96, v97
	v_cvt_pk_bf16_f32 v97, v94, v95
	v_addc_co_u32_e32 v117, vcc, 0, v63, vcc
	global_store_dwordx2 v[116:117], v[96:97], off
	v_pk_mul_f32 v[94:95], v[158:159], v[102:103] op_sel_hi:[1,0]
	v_pk_mul_f32 v[96:97], v[112:113], v[102:103] op_sel_hi:[1,0]
	v_pk_fma_f32 v[94:95], v[94:95], v[128:129], v[132:133]
	v_pk_fma_f32 v[96:97], v[96:97], v[126:127], v[130:131]
	s_mov_b32 s6, 0x3a03000
	v_cvt_pk_bf16_f32 v96, v96, v97
	v_cvt_pk_bf16_f32 v97, v94, v95
	global_store_dwordx2 v[116:117], v[96:97], off offset:2048
	v_pk_mul_f32 v[94:95], v[160:161], v[114:115] op_sel_hi:[1,0]
	v_pk_mul_f32 v[96:97], v[124:125], v[114:115] op_sel_hi:[1,0]
	v_pk_fma_f32 v[94:95], v[94:95], v[128:129], v[132:133]
	v_pk_fma_f32 v[96:97], v[96:97], v[126:127], v[130:131]
	v_add_co_u32_e32 v112, vcc, s6, v62
	v_cvt_pk_bf16_f32 v96, v96, v97
	v_cvt_pk_bf16_f32 v97, v94, v95
	v_addc_co_u32_e32 v113, vcc, 0, v63, vcc
	v_pk_mul_f32 v[62:63], v[162:163], v[118:119] op_sel_hi:[1,0]
	v_pk_mul_f32 v[94:95], v[120:121], v[118:119] op_sel_hi:[1,0]
	v_pk_fma_f32 v[62:63], v[62:63], v[128:129], v[132:133]
	v_pk_fma_f32 v[94:95], v[94:95], v[126:127], v[130:131]
	global_store_dwordx2 v[104:105], v[150:151], off
	v_cvt_pk_bf16_f32 v94, v94, v95
	v_cvt_pk_bf16_f32 v95, v62, v63
	global_store_dwordx2 v[112:113], v[96:97], off
	global_store_dwordx2 v[112:113], v[94:95], off offset:2048
	s_nop 0
	v_pk_mul_f32 v[62:63], v[66:67], v[74:75] op_sel_hi:[1,0]
	v_pk_fma_f32 v[64:65], v[64:65], v[176:177], v[180:181]
	v_pk_fma_f32 v[62:63], v[62:63], v[178:179], v[182:183]
	v_cvt_pk_bf16_f32 v64, v64, v65
	v_cvt_pk_bf16_f32 v65, v62, v63
	global_store_dwordx2 v[104:105], v[64:65], off offset:512
	v_pk_mul_f32 v[62:63], v[106:107], v[78:79] op_sel_hi:[1,0]
	v_pk_mul_f32 v[64:65], v[68:69], v[78:79] op_sel_hi:[1,0]
	v_pk_fma_f32 v[62:63], v[62:63], v[178:179], v[182:183]
	v_pk_fma_f32 v[64:65], v[64:65], v[176:177], v[180:181]
	s_nop 0
	v_cvt_pk_bf16_f32 v64, v64, v65
	v_cvt_pk_bf16_f32 v65, v62, v63
	global_store_dwordx2 v[104:105], v[64:65], off offset:2560
	v_pk_mul_f32 v[62:63], v[110:111], v[82:83] op_sel_hi:[1,0]
	v_pk_mul_f32 v[64:65], v[72:73], v[82:83] op_sel_hi:[1,0]
	v_pk_fma_f32 v[62:63], v[62:63], v[178:179], v[182:183]
	v_pk_fma_f32 v[64:65], v[64:65], v[176:177], v[180:181]
	s_nop 0
	v_cvt_pk_bf16_f32 v64, v64, v65
	v_cvt_pk_bf16_f32 v65, v62, v63
	global_store_dwordx2 v[108:109], v[64:65], off offset:512
	v_pk_mul_f32 v[62:63], v[142:143], v[86:87] op_sel_hi:[1,0]
	v_pk_mul_f32 v[64:65], v[76:77], v[86:87] op_sel_hi:[1,0]
	v_pk_fma_f32 v[62:63], v[62:63], v[178:179], v[182:183]
	v_pk_fma_f32 v[64:65], v[64:65], v[176:177], v[180:181]
	s_nop 0
	v_cvt_pk_bf16_f32 v64, v64, v65
	v_cvt_pk_bf16_f32 v65, v62, v63
	global_store_dwordx2 v[108:109], v[64:65], off offset:2560
	v_pk_mul_f32 v[62:63], v[144:145], v[90:91] op_sel_hi:[1,0]
	v_pk_mul_f32 v[64:65], v[80:81], v[90:91] op_sel_hi:[1,0]
	v_pk_fma_f32 v[62:63], v[62:63], v[178:179], v[182:183]
	v_pk_fma_f32 v[64:65], v[64:65], v[176:177], v[180:181]
	s_nop 0
	v_cvt_pk_bf16_f32 v64, v64, v65
	v_cvt_pk_bf16_f32 v65, v62, v63
	global_store_dwordx2 v[116:117], v[64:65], off offset:512
	v_pk_mul_f32 v[62:63], v[146:147], v[102:103] op_sel_hi:[1,0]
	v_pk_mul_f32 v[64:65], v[84:85], v[102:103] op_sel_hi:[1,0]
	v_pk_fma_f32 v[62:63], v[62:63], v[178:179], v[182:183]
	v_pk_fma_f32 v[64:65], v[64:65], v[176:177], v[180:181]
	s_nop 0
	v_cvt_pk_bf16_f32 v64, v64, v65
	v_cvt_pk_bf16_f32 v65, v62, v63
	global_store_dwordx2 v[116:117], v[64:65], off offset:2560
	v_pk_mul_f32 v[62:63], v[148:149], v[114:115] op_sel_hi:[1,0]
	v_pk_mul_f32 v[64:65], v[88:89], v[114:115] op_sel_hi:[1,0]
	v_pk_fma_f32 v[62:63], v[62:63], v[178:179], v[182:183]
	v_pk_fma_f32 v[64:65], v[64:65], v[176:177], v[180:181]
	s_nop 0
	v_cvt_pk_bf16_f32 v64, v64, v65
	v_cvt_pk_bf16_f32 v65, v62, v63
	global_store_dwordx2 v[112:113], v[64:65], off offset:512
	v_pk_mul_f32 v[62:63], v[122:123], v[118:119] op_sel_hi:[1,0]
	v_pk_mul_f32 v[64:65], v[92:93], v[118:119] op_sel_hi:[1,0]
	v_pk_fma_f32 v[62:63], v[62:63], v[178:179], v[182:183]
	v_pk_fma_f32 v[64:65], v[64:65], v[176:177], v[180:181]
	s_nop 0
	v_cvt_pk_bf16_f32 v64, v64, v65
	v_cvt_pk_bf16_f32 v65, v62, v63
	global_store_dwordx2 v[112:113], v[64:65], off offset:2560
	s_nop 0
	v_pk_fma_f32 v[34:35], v[34:35], v[186:187], v[194:195]
	v_pk_fma_f32 v[32:33], v[32:33], v[184:185], v[192:193]
	s_nop 0
	v_cvt_pk_bf16_f32 v32, v32, v33
	v_cvt_pk_bf16_f32 v33, v34, v35
	global_store_dwordx2 v[104:105], v[32:33], off offset:1024
	v_pk_mul_f32 v[32:33], v[38:39], v[78:79] op_sel_hi:[1,0]
	v_pk_mul_f32 v[34:35], v[36:37], v[78:79] op_sel_hi:[1,0]
	v_pk_fma_f32 v[32:33], v[32:33], v[186:187], v[194:195]
	v_pk_fma_f32 v[34:35], v[34:35], v[184:185], v[192:193]
	s_nop 0
	v_cvt_pk_bf16_f32 v34, v34, v35
	v_cvt_pk_bf16_f32 v35, v32, v33
	global_store_dwordx2 v[104:105], v[34:35], off offset:3072
	v_pk_mul_f32 v[32:33], v[42:43], v[82:83] op_sel_hi:[1,0]
	v_pk_mul_f32 v[34:35], v[40:41], v[82:83] op_sel_hi:[1,0]
	v_pk_fma_f32 v[32:33], v[32:33], v[186:187], v[194:195]
	v_pk_fma_f32 v[34:35], v[34:35], v[184:185], v[192:193]
	s_nop 0
	v_cvt_pk_bf16_f32 v34, v34, v35
	v_cvt_pk_bf16_f32 v35, v32, v33
	global_store_dwordx2 v[108:109], v[34:35], off offset:1024
	v_pk_mul_f32 v[32:33], v[46:47], v[86:87] op_sel_hi:[1,0]
	v_pk_mul_f32 v[34:35], v[44:45], v[86:87] op_sel_hi:[1,0]
	v_pk_fma_f32 v[32:33], v[32:33], v[186:187], v[194:195]
	v_pk_fma_f32 v[34:35], v[34:35], v[184:185], v[192:193]
	s_nop 0
	v_cvt_pk_bf16_f32 v34, v34, v35
	v_cvt_pk_bf16_f32 v35, v32, v33
	global_store_dwordx2 v[108:109], v[34:35], off offset:3072
	v_pk_mul_f32 v[32:33], v[50:51], v[90:91] op_sel_hi:[1,0]
	v_pk_mul_f32 v[34:35], v[48:49], v[90:91] op_sel_hi:[1,0]
	v_pk_fma_f32 v[32:33], v[32:33], v[186:187], v[194:195]
	v_pk_fma_f32 v[34:35], v[34:35], v[184:185], v[192:193]
	s_nop 0
	v_cvt_pk_bf16_f32 v34, v34, v35
	v_cvt_pk_bf16_f32 v35, v32, v33
	global_store_dwordx2 v[116:117], v[34:35], off offset:1024
	v_pk_mul_f32 v[32:33], v[54:55], v[102:103] op_sel_hi:[1,0]
	v_pk_mul_f32 v[34:35], v[52:53], v[102:103] op_sel_hi:[1,0]
	v_pk_fma_f32 v[32:33], v[32:33], v[186:187], v[194:195]
	v_pk_fma_f32 v[34:35], v[34:35], v[184:185], v[192:193]
	s_nop 0
	v_cvt_pk_bf16_f32 v34, v34, v35
	v_cvt_pk_bf16_f32 v35, v32, v33
	global_store_dwordx2 v[116:117], v[34:35], off offset:3072
	v_pk_mul_f32 v[32:33], v[58:59], v[114:115] op_sel_hi:[1,0]
	v_pk_mul_f32 v[34:35], v[56:57], v[114:115] op_sel_hi:[1,0]
	v_pk_fma_f32 v[32:33], v[32:33], v[186:187], v[194:195]
	v_pk_fma_f32 v[34:35], v[34:35], v[184:185], v[192:193]
	s_nop 0
	v_cvt_pk_bf16_f32 v34, v34, v35
	v_cvt_pk_bf16_f32 v35, v32, v33
	global_store_dwordx2 v[112:113], v[34:35], off offset:1024
	v_pk_mul_f32 v[32:33], v[70:71], v[118:119] op_sel_hi:[1,0]
	v_pk_mul_f32 v[34:35], v[60:61], v[118:119] op_sel_hi:[1,0]
	v_pk_fma_f32 v[32:33], v[32:33], v[186:187], v[194:195]
	v_pk_fma_f32 v[34:35], v[34:35], v[184:185], v[192:193]
	s_nop 0
	v_cvt_pk_bf16_f32 v34, v34, v35
	v_cvt_pk_bf16_f32 v35, v32, v33
	global_store_dwordx2 v[112:113], v[34:35], off offset:3072
	s_nop 0
	v_pk_fma_f32 v[2:3], v[2:3], v[198:199], v[202:203]
	v_pk_fma_f32 v[0:1], v[0:1], v[196:197], v[200:201]
	s_nop 0
	v_cvt_pk_bf16_f32 v0, v0, v1
	v_cvt_pk_bf16_f32 v1, v2, v3
	global_store_dwordx2 v[104:105], v[0:1], off offset:1536
	v_pk_mul_f32 v[0:1], v[6:7], v[78:79] op_sel_hi:[1,0]
	v_pk_mul_f32 v[2:3], v[4:5], v[78:79] op_sel_hi:[1,0]
	v_pk_fma_f32 v[0:1], v[0:1], v[198:199], v[202:203]
	v_pk_fma_f32 v[2:3], v[2:3], v[196:197], v[200:201]
	s_nop 0
	v_cvt_pk_bf16_f32 v2, v2, v3
	v_cvt_pk_bf16_f32 v3, v0, v1
	global_store_dwordx2 v[104:105], v[2:3], off offset:3584
	v_pk_mul_f32 v[0:1], v[10:11], v[82:83] op_sel_hi:[1,0]
	v_pk_mul_f32 v[2:3], v[8:9], v[82:83] op_sel_hi:[1,0]
	v_pk_fma_f32 v[0:1], v[0:1], v[198:199], v[202:203]
	v_pk_fma_f32 v[2:3], v[2:3], v[196:197], v[200:201]
	s_nop 0
	v_cvt_pk_bf16_f32 v2, v2, v3
	v_cvt_pk_bf16_f32 v3, v0, v1
	global_store_dwordx2 v[108:109], v[2:3], off offset:1536
	v_pk_mul_f32 v[0:1], v[14:15], v[86:87] op_sel_hi:[1,0]
	v_pk_mul_f32 v[2:3], v[12:13], v[86:87] op_sel_hi:[1,0]
	v_pk_fma_f32 v[0:1], v[0:1], v[198:199], v[202:203]
	v_pk_fma_f32 v[2:3], v[2:3], v[196:197], v[200:201]
	s_nop 0
	v_cvt_pk_bf16_f32 v2, v2, v3
	v_cvt_pk_bf16_f32 v3, v0, v1
	global_store_dwordx2 v[108:109], v[2:3], off offset:3584
	v_pk_mul_f32 v[0:1], v[18:19], v[90:91] op_sel_hi:[1,0]
	v_pk_mul_f32 v[2:3], v[16:17], v[90:91] op_sel_hi:[1,0]
	v_pk_fma_f32 v[0:1], v[0:1], v[198:199], v[202:203]
	v_pk_fma_f32 v[2:3], v[2:3], v[196:197], v[200:201]
	s_nop 0
	v_cvt_pk_bf16_f32 v2, v2, v3
	v_cvt_pk_bf16_f32 v3, v0, v1
	global_store_dwordx2 v[116:117], v[2:3], off offset:1536
	v_pk_mul_f32 v[0:1], v[22:23], v[102:103] op_sel_hi:[1,0]
	v_pk_mul_f32 v[2:3], v[20:21], v[102:103] op_sel_hi:[1,0]
	v_pk_fma_f32 v[0:1], v[0:1], v[198:199], v[202:203]
	v_pk_fma_f32 v[2:3], v[2:3], v[196:197], v[200:201]
	s_nop 0
	v_cvt_pk_bf16_f32 v2, v2, v3
	v_cvt_pk_bf16_f32 v3, v0, v1
	global_store_dwordx2 v[116:117], v[2:3], off offset:3584
	v_pk_mul_f32 v[0:1], v[26:27], v[114:115] op_sel_hi:[1,0]
	v_pk_mul_f32 v[2:3], v[24:25], v[114:115] op_sel_hi:[1,0]
	v_pk_fma_f32 v[0:1], v[0:1], v[198:199], v[202:203]
	v_pk_fma_f32 v[2:3], v[2:3], v[196:197], v[200:201]
	s_nop 0
	v_cvt_pk_bf16_f32 v2, v2, v3
	v_cvt_pk_bf16_f32 v3, v0, v1
	global_store_dwordx2 v[112:113], v[2:3], off offset:1536
	v_pk_mul_f32 v[0:1], v[30:31], v[118:119] op_sel_hi:[1,0]
	v_pk_mul_f32 v[2:3], v[28:29], v[118:119] op_sel_hi:[1,0]
	v_pk_fma_f32 v[0:1], v[0:1], v[198:199], v[202:203]
	v_pk_fma_f32 v[2:3], v[2:3], v[196:197], v[200:201]
	s_nop 0
	v_cvt_pk_bf16_f32 v2, v2, v3
	v_cvt_pk_bf16_f32 v3, v0, v1
	global_store_dwordx2 v[112:113], v[2:3], off offset:3584
	s_cbranch_scc1 .LBB0_1575
